# static s_setprio 1 for waves 4-7 (younger half) around the prompt-attention tile loop, reset at loop exit; on top of the P7 epilogue lane remap
# speedup vs baseline: 1.0058x; 1.0058x over previous
; #define LAS __attribute__((address_space(3)))
; template <bool SAMPLE>
; __device__ __forceinline__ void attn_unit(const Params& p, LAS unsigned char* lds, int unit, int tid, int lane, int wave, float thr) {
;     ...
;     bf16x8 qf[5];
;     { const bf16_t* qp = Qw + (qrow0 + qoff + r32) * 1024 + head * 64 + 8 * h2;
; #pragma unroll
;       for (int ks = 0; ks < 4; ++ks) qf[ks] = *(const bf16x8*)(qp + 16 * ks);
;       const short one = h2 == 0 ? (short)0x3f80 : (short)0; qf[4] = (bf16x8){one, one, one, 0, 0, 0, 0, 0}; }
;     const int qpos = t0 + qoff + r32;
;     float mrun = -INFINITY, lrun = 0.f; f32x16 o0 = {}, o1 = {};
;     u32x4 kreg[SAMPLE ? 4 : 1], vreg[SAMPLE ? 4 : 1]; float freg = 0.f;
;     const bool active = !SAMPLE || wave < 4;
;     ...
;     const LAS unsigned char* kbase = Kt + slot * TILEB + r32 * KROW + 16 * h2;
;     const LAS unsigned char* vbase = Vt + slot * TILEB + (4 * h2 + ((lane & 15) >> 2)) * KROW + (16 * ((lane >> 4) & 1) + 4 * (lane & 3)) * 2;
;     const int qmax_w = t0 + qoff + 31;
.LBB0_609:
	s_or_b64 exec, exec, s[10:11]
	v_lshlrev_b32_e32 v100, 2, v11
	v_lshrrev_b32_e32 v3, 2, v9
	v_and_or_b32 v3, v3, 3, v100
	v_mul_lo_u32 v3, v3, s48
	v_cmp_gt_u32_e32 vcc, 32, v9
	v_add_u32_e32 v20, 0, v3
	v_and_b32_e32 v3, 16, v9
	v_lshlrev_b32_e32 v5, 2, v9
	s_lshl_b32 s10, s9, 1
	s_and_b32 s9, s9, 63
	v_cndmask_b32_e32 v2, 0, v230, vcc
	v_and_or_b32 v3, v5, 12, v3
	s_lshl_b32 s34, s9, 2
	s_mov_b32 s9, s35
	s_add_i32 s14, s33, s14
	v_lshlrev_b32_e32 v21, 1, v3
	v_perm_b32 v95, 0, v2, v231
	v_perm_b32 v94, v2, v2, s53
	v_lshlrev_b64 v[2:3], 11, v[6:7]
	v_mov_b64_e32 v[6:7], s[8:9]
	s_add_i32 s7, s15, 4
	s_or_b32 s15, s14, 31
	s_and_b32 s10, s10, 0x780
	v_cmp_lt_u64_e32 vcc, s[34:35], v[6:7]
	v_or3_b32 v2, v2, s10, v12
	s_and_b64 s[10:11], vcc, exec
	s_cselect_b32 s8, s34, s8
	v_lshl_add_u64 v[2:3], s[80:81], 0, v[2:3]
	s_lshl_b32 s34, s8, 17
	v_mov_b32_e32 v16, v4
	v_mov_b32_e32 v17, v4
	v_or_b32_e32 v106, s14, v10
	v_mad_u32_u24 v107, v10, s48, 0
	v_lshlrev_b32_e32 v19, 4, v11
	v_add_u32_e32 v108, 64, v8
	v_lshl_add_u64 v[102:103], v[2:3], 0, s[34:35]
	v_mov_b32_e32 v2, v4
	v_mov_b32_e32 v3, v4
	v_mov_b32_e32 v5, v4
	v_mov_b32_e32 v6, v4
	v_mov_b32_e32 v7, v4
	v_mov_b32_e32 v8, v4
	v_mov_b32_e32 v9, v4
	v_mov_b32_e32 v10, v4
	v_mov_b32_e32 v11, v4
	v_mov_b32_e32 v12, v4
	v_mov_b32_e32 v13, v4
	v_mov_b32_e32 v14, v4
	v_mov_b32_e32 v15, v4
	v_mov_b64_e32 v[36:37], v[16:17]
	v_add_u32_e32 v110, v107, v19
	v_add_u32_e32 v111, v20, v21
	v_add_u32_e32 v112, 0, v18
	v_mov_b64_e32 v[34:35], v[14:15]
	v_mov_b64_e32 v[32:33], v[12:13]
	v_mov_b64_e32 v[30:31], v[10:11]
	v_mov_b64_e32 v[28:29], v[8:9]
	v_mov_b64_e32 v[26:27], v[6:7]
	v_mov_b64_e32 v[24:25], v[4:5]
	v_mov_b64_e32 v[22:23], v[2:3]
	v_mov_b64_e32 v[20:21], v[16:17]
	v_mov_b32_e32 v96, s56
	v_mov_b32_e32 v97, s56
	s_add_i32 s33, s13, 1
	v_mov_b32_e32 v113, 0xff800000
	v_mov_b32_e32 v109, 0
	v_mov_b64_e32 v[18:19], v[14:15]
	v_mov_b64_e32 v[16:17], v[12:13]
	v_mov_b64_e32 v[14:15], v[10:11]
	v_mov_b64_e32 v[12:13], v[8:9]
	v_mov_b64_e32 v[10:11], v[6:7]
	v_mov_b64_e32 v[8:9], v[4:5]
	v_mov_b64_e32 v[6:7], v[2:3]
	s_cmp_lt_u32 s85, 4
	s_cbranch_scc1 .Lpa_prio_skip
	s_setprio 1
.Lpa_prio_skip:
	s_waitcnt lgkmcnt(0)
	s_barrier
	s_branch .LBB0_612

; __device__ __forceinline__ unsigned pk2(float lo, float hi) { f32x2_t v = {lo, hi}; bf16x2_t b = __builtin_convertvector(v, bf16x2_t); return __builtin_bit_cast(unsigned, b); }
; template <bool SAMPLE>
; __device__ __forceinline__ void attn_unit(const Params& p, LAS unsigned char* lds, int unit, int tid, int lane, int wave, float thr) {
;     ...
;     if (!active) return;
;     const float ltot = lrun + __shfl_xor(lrun, 32); const float inv = 1.0f / ltot;
;     bf16_t* orow = (bf16_t*)(p.ws + WS_MIX) + (qrow0 + qoff + r32) * DM + head * 64 + 4 * h2;
; #pragma unroll
;     for (int g = 0; g < 4; ++g) {
;         u32x2 w0, w1; w0.x = pk2(o0[4 * g] * inv, o0[4 * g + 1] * inv); w0.y = pk2(o0[4 * g + 2] * inv, o0[4 * g + 3] * inv);
;         w1.x = pk2(o1[4 * g] * inv, o1[4 * g + 1] * inv); w1.y = pk2(o1[4 * g + 2] * inv, o1[4 * g + 3] * inv);
;         *(u32x2*)(orow + 8 * g) = w0; *(u32x2*)(orow + 32 + 8 * g) = w1;
;     }
.LBB0_623:
	s_setprio 0
	v_xor_b32_e32 v2, 32, v216
	v_add_u32_e32 v3, 64, v217
	v_cmp_lt_i32_e32 vcc, v2, v3
	s_lshl_b32 s34, s12, 1
	v_ashrrev_i32_e32 v101, 31, v100
	v_cndmask_b32_e32 v2, v216, v2, vcc
	v_lshlrev_b32_e32 v2, 2, v2
	ds_bpermute_b32 v2, v2, v109
	s_waitcnt lgkmcnt(0)
	v_add_f32_e32 v5, v109, v2
	v_div_scale_f32 v38, s[2:3], v5, v5, 1.0
	v_rcp_f32_e32 v39, v38
	v_div_scale_f32 v40, vcc, 1.0, v5, 1.0
	v_readlane_b32 s2, v254, 41
	v_fma_f32 v41, -v38, v39, 1.0
	v_fmac_f32_e32 v39, v41, v39
	v_mul_f32_e32 v41, v40, v39
	v_fma_f32 v42, -v38, v41, v40
	v_fmac_f32_e32 v41, v42, v39
	v_fma_f32 v38, -v38, v41, v40
	v_lshlrev_b64 v[2:3], 12, v[98:99]
	v_div_fmas_f32 v38, v38, v39, v41
	v_readlane_b32 s3, v254, 42
	v_div_fixup_f32 v38, v38, v5, 1.0
	v_pk_mul_f32 v[22:23], v[22:23], v[38:39] op_sel_hi:[1,0]
	v_lshl_add_u64 v[2:3], s[2:3], 0, v[2:3]
	v_lshl_add_u64 v[2:3], v[2:3], 0, s[34:35]
	v_pk_mul_f32 v[24:25], v[24:25], v[38:39] op_sel_hi:[1,0]
	v_pk_mul_f32 v[6:7], v[6:7], v[38:39] op_sel_hi:[1,0]
	v_pk_mul_f32 v[8:9], v[8:9], v[38:39] op_sel_hi:[1,0]
	v_lshl_add_u64 v[2:3], v[100:101], 1, v[2:3]
	v_cvt_pk_bf16_f32 v22, v22, v23
	v_cvt_pk_bf16_f32 v23, v24, v25
	v_cvt_pk_bf16_f32 v6, v6, v7
	v_cvt_pk_bf16_f32 v7, v8, v9
	global_store_dwordx2 v[2:3], v[22:23], off
	global_store_dwordx2 v[2:3], v[6:7], off offset:64
	v_pk_mul_f32 v[6:7], v[26:27], v[38:39] op_sel_hi:[1,0]
	v_pk_mul_f32 v[8:9], v[28:29], v[38:39] op_sel_hi:[1,0]
	v_cvt_pk_bf16_f32 v6, v6, v7
	v_cvt_pk_bf16_f32 v7, v8, v9
	v_pk_mul_f32 v[8:9], v[10:11], v[38:39] op_sel_hi:[1,0]
	v_pk_mul_f32 v[10:11], v[12:13], v[38:39] op_sel_hi:[1,0]
	v_cvt_pk_bf16_f32 v8, v8, v9
	v_cvt_pk_bf16_f32 v9, v10, v11
	global_store_dwordx2 v[2:3], v[6:7], off offset:16
	global_store_dwordx2 v[2:3], v[8:9], off offset:80
	v_pk_mul_f32 v[6:7], v[30:31], v[38:39] op_sel_hi:[1,0]
	v_pk_mul_f32 v[8:9], v[32:33], v[38:39] op_sel_hi:[1,0]
	v_cvt_pk_bf16_f32 v6, v6, v7
	v_cvt_pk_bf16_f32 v7, v8, v9
	v_pk_mul_f32 v[8:9], v[14:15], v[38:39] op_sel_hi:[1,0]
	v_pk_mul_f32 v[10:11], v[16:17], v[38:39] op_sel_hi:[1,0]
	v_cvt_pk_bf16_f32 v8, v8, v9
	v_cvt_pk_bf16_f32 v9, v10, v11
	global_store_dwordx2 v[2:3], v[6:7], off offset:32
	global_store_dwordx2 v[2:3], v[8:9], off offset:96
	v_pk_mul_f32 v[6:7], v[34:35], v[38:39] op_sel_hi:[1,0]
	v_pk_mul_f32 v[8:9], v[36:37], v[38:39] op_sel_hi:[1,0]
	v_cvt_pk_bf16_f32 v6, v6, v7
	v_cvt_pk_bf16_f32 v7, v8, v9
	v_pk_mul_f32 v[8:9], v[18:19], v[38:39] op_sel_hi:[1,0]
	v_pk_mul_f32 v[10:11], v[20:21], v[38:39] op_sel_hi:[1,0]
	v_cvt_pk_bf16_f32 v8, v8, v9
	v_cvt_pk_bf16_f32 v9, v10, v11
	global_store_dwordx2 v[2:3], v[6:7], off offset:48
	global_store_dwordx2 v[2:3], v[8:9], off offset:112
